# v36 + F1 K loop: first two phases of every unit after the first run from a peeled copy whose counted waits tolerate the 8 epilogue stores still in flight (vmcnt 8 -> 16)
# baseline (speedup 1.0000x reference)
.LBB0_857:
	s_cmp_lt_i32 s94, 7
	s_cselect_b64 s[0:1], -1, 0
	s_cmp_gt_i32 s95, 6
	s_cselect_b64 s[2:3], -1, 0
	s_and_b64 s[0:1], s[0:1], s[2:3]
	s_andn2_b64 vcc, exec, s[0:1]
	s_cbranch_vccnz .LBB0_998
	s_mov_b32 s99, 0
	s_mov_b64 s[0:1], s[76:77]
	s_waitcnt lgkmcnt(0)
	s_load_dwordx2 s[4:5], s[0:1], 0xb0
	s_mov_b64 s[0:1], s[76:77]
	v_mov_b32_e32 v0, v216
	s_load_dword s0, s[76:77], 0xc0
	s_add_u32 s2, s76, 0xc0
	s_addc_u32 s3, s77, 0
	s_waitcnt lgkmcnt(0)
	s_add_u32 s29, s4, 0x2bb00000
	s_addc_u32 s30, s5, 0
	s_add_u32 s31, s4, 0x1400000
	s_mov_b32 s1, s0
	s_mov_b32 s28, s72
	s_addc_u32 s33, s5, 0
	s_waitcnt vmcnt(0)
	v_mov_b32_e32 v8, v216
	s_cmpk_lt_i32 s28, 0x200
	s_cselect_b64 s[8:9], -1, 0
	s_cmpk_gt_i32 s28, 0x1ff
	v_readfirstlane_b32 s14, v8
	s_cbranch_scc1 .LBB0_861
	s_ashr_i32 s6, s28, 31
	s_lshr_b32 s6, s6, 29
	s_add_i32 s12, s28, s6
	s_and_b32 s6, s12, -8
	s_sub_i32 s10, s28, s6
	s_cmp_gt_i32 s10, -1
	s_cbranch_scc0 .LBB0_862
	s_lshl_b32 s11, s10, 6
	s_ashr_i32 s6, s12, 3
	s_cbranch_execz .LBB0_863
	s_branch .LBB0_864

.LBB0_876:
	s_add_u32 s17, s24, 0x100
	s_addc_u32 s50, s25, 0
	s_add_u32 s22, s22, 0x40080
	v_mov_b32_e32 v0, 0
	s_addc_u32 s23, s23, 0
	s_mov_b32 s51, -2
	v_mov_b32_e32 v1, v0
	v_mov_b32_e32 v2, v0
	v_mov_b32_e32 v3, v0
	v_mov_b32_e32 v4, v0
	v_mov_b32_e32 v5, v0
	v_mov_b32_e32 v6, v0
	v_mov_b32_e32 v7, v0
	v_mov_b32_e32 v16, v0
	v_mov_b32_e32 v17, v0
	v_mov_b32_e32 v18, v0
	v_mov_b32_e32 v19, v0
	v_mov_b32_e32 v20, v0
	v_mov_b32_e32 v21, v0
	v_mov_b32_e32 v22, v0
	v_mov_b32_e32 v23, v0
	v_mov_b32_e32 v32, v0
	v_mov_b32_e32 v33, v0
	v_mov_b32_e32 v34, v0
	v_mov_b32_e32 v35, v0
	v_mov_b32_e32 v36, v0
	v_mov_b32_e32 v37, v0
	v_mov_b32_e32 v38, v0
	v_mov_b32_e32 v39, v0
	v_mov_b32_e32 v48, v0
	v_mov_b32_e32 v49, v0
	v_mov_b32_e32 v50, v0
	v_mov_b32_e32 v51, v0
	v_mov_b32_e32 v52, v0
	v_mov_b32_e32 v53, v0
	v_mov_b32_e32 v54, v0
	v_mov_b32_e32 v55, v0
	v_mov_b32_e32 v8, v0
	v_mov_b32_e32 v9, v0
	v_mov_b32_e32 v10, v0
	v_mov_b32_e32 v11, v0
	v_mov_b32_e32 v12, v0
	v_mov_b32_e32 v13, v0
	v_mov_b32_e32 v14, v0
	v_mov_b32_e32 v15, v0
	v_mov_b32_e32 v24, v0
	v_mov_b32_e32 v25, v0
	v_mov_b32_e32 v26, v0
	v_mov_b32_e32 v27, v0
	v_mov_b32_e32 v28, v0
	v_mov_b32_e32 v29, v0
	v_mov_b32_e32 v30, v0
	v_mov_b32_e32 v31, v0
	v_mov_b32_e32 v40, v0
	v_mov_b32_e32 v41, v0
	v_mov_b32_e32 v42, v0
	v_mov_b32_e32 v43, v0
	v_mov_b32_e32 v44, v0
	v_mov_b32_e32 v45, v0
	v_mov_b32_e32 v46, v0
	v_mov_b32_e32 v47, v0
	v_mov_b32_e32 v56, v0
	v_mov_b32_e32 v57, v0
	v_mov_b32_e32 v58, v0
	v_mov_b32_e32 v59, v0
	v_mov_b32_e32 v60, v0
	v_mov_b32_e32 v61, v0
	v_mov_b32_e32 v62, v0
	v_mov_b32_e32 v63, v0
	v_mov_b32_e32 v72, v0
	v_mov_b32_e32 v73, v0
	v_mov_b32_e32 v74, v0
	v_mov_b32_e32 v75, v0
	v_mov_b32_e32 v76, v0
	v_mov_b32_e32 v77, v0
	v_mov_b32_e32 v78, v0
	v_mov_b32_e32 v79, v0
	v_mov_b32_e32 v96, v0
	v_mov_b32_e32 v97, v0
	v_mov_b32_e32 v98, v0
	v_mov_b32_e32 v99, v0
	v_mov_b32_e32 v104, v0
	v_mov_b32_e32 v105, v0
	v_mov_b32_e32 v106, v0
	v_mov_b32_e32 v107, v0
	v_mov_b32_e32 v124, v0
	v_mov_b32_e32 v125, v0
	v_mov_b32_e32 v126, v0
	v_mov_b32_e32 v127, v0
	v_mov_b32_e32 v128, v0
	v_mov_b32_e32 v129, v0
	v_mov_b32_e32 v130, v0
	v_mov_b32_e32 v131, v0
	v_mov_b32_e32 v144, v0
	v_mov_b32_e32 v145, v0
	v_mov_b32_e32 v146, v0
	v_mov_b32_e32 v147, v0
	v_mov_b32_e32 v148, v0
	v_mov_b32_e32 v149, v0
	v_mov_b32_e32 v150, v0
	v_mov_b32_e32 v151, v0
	v_mov_b32_e32 v84, v0
	v_mov_b32_e32 v85, v0
	v_mov_b32_e32 v86, v0
	v_mov_b32_e32 v87, v0
	v_mov_b32_e32 v92, v0
	v_mov_b32_e32 v93, v0
	v_mov_b32_e32 v94, v0
	v_mov_b32_e32 v95, v0
	v_mov_b32_e32 v112, v0
	v_mov_b32_e32 v113, v0
	v_mov_b32_e32 v114, v0
	v_mov_b32_e32 v115, v0
	v_mov_b32_e32 v116, v0
	v_mov_b32_e32 v117, v0
	v_mov_b32_e32 v118, v0
	v_mov_b32_e32 v119, v0
	v_mov_b32_e32 v136, v0
	v_mov_b32_e32 v137, v0
	v_mov_b32_e32 v138, v0
	v_mov_b32_e32 v139, v0
	v_mov_b32_e32 v140, v0
	v_mov_b32_e32 v141, v0
	v_mov_b32_e32 v142, v0
	v_mov_b32_e32 v143, v0
	v_mov_b32_e32 v152, v0
	v_mov_b32_e32 v153, v0
	v_mov_b32_e32 v154, v0
	v_mov_b32_e32 v155, v0
	v_mov_b32_e32 v156, v0
	v_mov_b32_e32 v157, v0
	v_mov_b32_e32 v158, v0
	v_mov_b32_e32 v159, v0
	s_cmp_eq_u32 s99, 0
	s_cbranch_scc1 .LBB0_877
	ds_read_b128 v[64:67], v223
	ds_read_b128 v[68:71], v223 offset:1024
	ds_read_b128 v[80:83], v223 offset:2048
	ds_read_b128 v[88:91], v223 offset:3072
	ds_read_b128 v[100:103], v224
	ds_read_b128 v[108:111], v224 offset:1024
	ds_read_b128 v[120:123], v224 offset:2048
	ds_read_b128 v[132:135], v224 offset:3072
	s_add_u32 s24, s22, 0xfffc0080
	s_addc_u32 s25, s23, -1
	s_cmp_eq_u32 s51, 12
	s_cselect_b32 s27, s19, s25
	s_cselect_b32 s26, s18, s24
	s_cselect_b32 s25, s21, s50
	s_cselect_b32 s24, s20, s17
	v_lshl_add_u64 v[208:209], s[22:23], 0, v[202:203]
	s_add_i32 m0, s35, 0xc000
	ds_read_b128 v[160:163], v225
	ds_read_b128 v[164:167], v225 offset:1024
	ds_read_b128 v[168:171], v225 offset:2048
	ds_read_b128 v[172:175], v225 offset:3072
	ds_read_b128 v[176:179], v225 offset:4096
	ds_read_b128 v[180:183], v225 offset:5120
	ds_read_b128 v[184:187], v225 offset:6144
	ds_read_b128 v[188:191], v225 offset:7168
	global_load_lds_dwordx4 v[208:209], off
	v_lshl_add_u64 v[208:209], s[22:23], 0, v[200:201]
	s_add_i32 m0, s35, 0xe000
	s_nop 0
	global_load_lds_dwordx4 v[208:209], off
	s_waitcnt vmcnt(16)
	s_waitcnt lgkmcnt(0)
	s_barrier
	s_setprio 1
	s_waitcnt lgkmcnt(0)
	v_mfma_f32_16x16x32_bf16 v[156:159], v[64:67], v[160:163], v[156:159]
	v_mfma_f32_16x16x32_bf16 v[152:155], v[80:83], v[160:163], v[152:155]
	v_mfma_f32_16x16x32_bf16 v[140:143], v[64:67], v[168:171], v[140:143]
	v_mfma_f32_16x16x32_bf16 v[136:139], v[80:83], v[168:171], v[136:139]
	v_mfma_f32_16x16x32_bf16 v[116:119], v[64:67], v[176:179], v[116:119]
	v_mfma_f32_16x16x32_bf16 v[112:115], v[80:83], v[176:179], v[112:115]
	v_mfma_f32_16x16x32_bf16 v[92:95], v[64:67], v[184:187], v[92:95]
	v_mfma_f32_16x16x32_bf16 v[84:87], v[80:83], v[184:187], v[84:87]
	v_mfma_f32_16x16x32_bf16 v[156:159], v[68:71], v[164:167], v[156:159]
	v_mfma_f32_16x16x32_bf16 v[152:155], v[88:91], v[164:167], v[152:155]
	v_mfma_f32_16x16x32_bf16 v[140:143], v[68:71], v[172:175], v[140:143]
	v_mfma_f32_16x16x32_bf16 v[136:139], v[88:91], v[172:175], v[136:139]
	v_mfma_f32_16x16x32_bf16 v[116:119], v[68:71], v[180:183], v[116:119]
	v_mfma_f32_16x16x32_bf16 v[112:115], v[88:91], v[180:183], v[112:115]
	v_mfma_f32_16x16x32_bf16 v[92:95], v[68:71], v[188:191], v[92:95]
	v_mfma_f32_16x16x32_bf16 v[84:87], v[88:91], v[188:191], v[84:87]
	s_setprio 0
	s_setprio 1
	v_mfma_f32_16x16x32_bf16 v[148:151], v[100:103], v[160:163], v[148:151]
	v_mfma_f32_16x16x32_bf16 v[144:147], v[120:123], v[160:163], v[144:147]
	v_mfma_f32_16x16x32_bf16 v[128:131], v[100:103], v[168:171], v[128:131]
	v_mfma_f32_16x16x32_bf16 v[124:127], v[120:123], v[168:171], v[124:127]
	v_mfma_f32_16x16x32_bf16 v[104:107], v[100:103], v[176:179], v[104:107]
	v_mfma_f32_16x16x32_bf16 v[96:99], v[120:123], v[176:179], v[96:99]
	v_mfma_f32_16x16x32_bf16 v[76:79], v[100:103], v[184:187], v[76:79]
	v_mfma_f32_16x16x32_bf16 v[72:75], v[120:123], v[184:187], v[72:75]
	v_mfma_f32_16x16x32_bf16 v[148:151], v[108:111], v[164:167], v[148:151]
	v_mfma_f32_16x16x32_bf16 v[144:147], v[132:135], v[164:167], v[144:147]
	v_mfma_f32_16x16x32_bf16 v[128:131], v[108:111], v[172:175], v[128:131]
	v_mfma_f32_16x16x32_bf16 v[124:127], v[132:135], v[172:175], v[124:127]
	v_mfma_f32_16x16x32_bf16 v[104:107], v[108:111], v[180:183], v[104:107]
	v_mfma_f32_16x16x32_bf16 v[96:99], v[132:135], v[180:183], v[96:99]
	v_mfma_f32_16x16x32_bf16 v[76:79], v[108:111], v[188:191], v[76:79]
	v_mfma_f32_16x16x32_bf16 v[72:75], v[132:135], v[188:191], v[72:75]
	s_setprio 0
	s_barrier
	s_add_i32 s52, s44, s34
	v_lshl_add_u64 v[208:209], s[24:25], 0, v[194:195]
	s_mov_b32 m0, s52
	ds_read_b128 v[160:163], v225 offset:16384
	ds_read_b128 v[164:167], v225 offset:17408
	ds_read_b128 v[168:171], v225 offset:18432
	ds_read_b128 v[172:175], v225 offset:19456
	ds_read_b128 v[176:179], v225 offset:20480
	ds_read_b128 v[180:183], v225 offset:21504
	ds_read_b128 v[184:187], v225 offset:22528
	ds_read_b128 v[188:191], v225 offset:23552
	global_load_lds_dwordx4 v[208:209], off
	s_add_i32 m0, s52, 0x2000
	s_add_u32 s52, s24, 0x40000
	v_lshl_add_u64 v[210:211], s[24:25], 0, v[198:199]
	s_addc_u32 s53, s25, 0
	s_add_i32 s54, s45, s34
	global_load_lds_dwordx4 v[210:211], off
	v_lshl_add_u64 v[212:213], s[52:53], 0, v[194:195]
	s_mov_b32 m0, s54
	v_lshl_add_u64 v[214:215], s[26:27], 0, v[196:197]
	global_load_lds_dwordx4 v[212:213], off
	v_lshl_add_u64 v[212:213], s[52:53], 0, v[198:199]
	s_add_i32 m0, s54, 0x2000
	s_nop 0
	global_load_lds_dwordx4 v[212:213], off
	v_lshl_add_u64 v[212:213], s[26:27], 0, v[192:193]
	s_mov_b32 m0, s35
	s_nop 0
	global_load_lds_dwordx4 v[212:213], off
	s_mov_b32 m0, s36
	s_nop 0
	global_load_lds_dwordx4 v[214:215], off
	s_waitcnt vmcnt(16)
	s_waitcnt lgkmcnt(0)
	s_barrier
	s_setprio 1
	s_waitcnt lgkmcnt(0)
	v_mfma_f32_16x16x32_bf16 v[60:63], v[64:67], v[160:163], v[60:63]
	v_mfma_f32_16x16x32_bf16 v[56:59], v[80:83], v[160:163], v[56:59]
	v_mfma_f32_16x16x32_bf16 v[44:47], v[64:67], v[168:171], v[44:47]
	v_mfma_f32_16x16x32_bf16 v[40:43], v[80:83], v[168:171], v[40:43]
	v_mfma_f32_16x16x32_bf16 v[28:31], v[64:67], v[176:179], v[28:31]
	v_mfma_f32_16x16x32_bf16 v[24:27], v[80:83], v[176:179], v[24:27]
	v_mfma_f32_16x16x32_bf16 v[12:15], v[64:67], v[184:187], v[12:15]
	v_mfma_f32_16x16x32_bf16 v[8:11], v[80:83], v[184:187], v[8:11]
	v_mfma_f32_16x16x32_bf16 v[60:63], v[68:71], v[164:167], v[60:63]
	v_mfma_f32_16x16x32_bf16 v[56:59], v[88:91], v[164:167], v[56:59]
	v_mfma_f32_16x16x32_bf16 v[44:47], v[68:71], v[172:175], v[44:47]
	v_mfma_f32_16x16x32_bf16 v[40:43], v[88:91], v[172:175], v[40:43]
	v_mfma_f32_16x16x32_bf16 v[28:31], v[68:71], v[180:183], v[28:31]
	v_mfma_f32_16x16x32_bf16 v[24:27], v[88:91], v[180:183], v[24:27]
	v_mfma_f32_16x16x32_bf16 v[12:15], v[68:71], v[188:191], v[12:15]
	v_mfma_f32_16x16x32_bf16 v[8:11], v[88:91], v[188:191], v[8:11]
	s_setprio 0
	s_setprio 1
	v_mfma_f32_16x16x32_bf16 v[52:55], v[100:103], v[160:163], v[52:55]
	v_mfma_f32_16x16x32_bf16 v[48:51], v[120:123], v[160:163], v[48:51]
	v_mfma_f32_16x16x32_bf16 v[36:39], v[100:103], v[168:171], v[36:39]
	v_mfma_f32_16x16x32_bf16 v[32:35], v[120:123], v[168:171], v[32:35]
	v_mfma_f32_16x16x32_bf16 v[20:23], v[100:103], v[176:179], v[20:23]
	v_mfma_f32_16x16x32_bf16 v[16:19], v[120:123], v[176:179], v[16:19]
	v_mfma_f32_16x16x32_bf16 v[4:7], v[100:103], v[184:187], v[4:7]
	v_mfma_f32_16x16x32_bf16 v[0:3], v[120:123], v[184:187], v[0:3]
	v_mfma_f32_16x16x32_bf16 v[52:55], v[108:111], v[164:167], v[52:55]
	v_mfma_f32_16x16x32_bf16 v[48:51], v[132:135], v[164:167], v[48:51]
	v_mfma_f32_16x16x32_bf16 v[36:39], v[108:111], v[172:175], v[36:39]
	v_mfma_f32_16x16x32_bf16 v[32:35], v[132:135], v[172:175], v[32:35]
	v_mfma_f32_16x16x32_bf16 v[20:23], v[108:111], v[180:183], v[20:23]
	v_mfma_f32_16x16x32_bf16 v[16:19], v[132:135], v[180:183], v[16:19]
	v_mfma_f32_16x16x32_bf16 v[4:7], v[108:111], v[188:191], v[4:7]
	v_mfma_f32_16x16x32_bf16 v[0:3], v[132:135], v[188:191], v[0:3]
	s_setprio 0
	s_barrier
	s_branch .Lpeel_mid_0

.Lpeel_mid_0:
	s_add_i32 s52, 0, 0x18000
	s_add_i32 s53, 0, 0x1c000
	v_add_u32_e32 v88, s52, v218
	v_add_u32_e32 v132, s53, v218
	ds_read_b128 v[64:67], v88
	ds_read_b128 v[68:71], v88 offset:1024
	ds_read_b128 v[80:83], v88 offset:2048
	ds_read_b128 v[88:91], v88 offset:3072
	ds_read_b128 v[100:103], v132
	ds_read_b128 v[108:111], v132 offset:1024
	ds_read_b128 v[120:123], v132 offset:2048
	ds_read_b128 v[132:135], v132 offset:3072
	s_add_u32 s26, s26, 0x40000
	s_addc_u32 s27, s27, 0
	s_mov_b32 m0, s37
	v_lshl_add_u64 v[226:227], s[26:27], 0, v[192:193]
	ds_read_b128 v[160:163], v225 offset:32768
	ds_read_b128 v[164:167], v225 offset:33792
	ds_read_b128 v[168:171], v225 offset:34816
	ds_read_b128 v[172:175], v225 offset:35840
	ds_read_b128 v[176:179], v225 offset:36864
	ds_read_b128 v[180:183], v225 offset:37888
	ds_read_b128 v[184:187], v225 offset:38912
	ds_read_b128 v[188:191], v225 offset:39936
	global_load_lds_dwordx4 v[226:227], off
	v_lshl_add_u64 v[226:227], s[26:27], 0, v[196:197]
	s_mov_b32 m0, s38
	s_nop 0
	global_load_lds_dwordx4 v[226:227], off
	s_waitcnt vmcnt(8)
	s_waitcnt lgkmcnt(0)
	s_barrier
	s_setprio 1
	s_waitcnt lgkmcnt(0)
	v_mfma_f32_16x16x32_bf16 v[156:159], v[64:67], v[160:163], v[156:159]
	v_mfma_f32_16x16x32_bf16 v[152:155], v[80:83], v[160:163], v[152:155]
	v_mfma_f32_16x16x32_bf16 v[140:143], v[64:67], v[168:171], v[140:143]
	v_mfma_f32_16x16x32_bf16 v[136:139], v[80:83], v[168:171], v[136:139]
	v_mfma_f32_16x16x32_bf16 v[116:119], v[64:67], v[176:179], v[116:119]
	v_mfma_f32_16x16x32_bf16 v[112:115], v[80:83], v[176:179], v[112:115]
	v_mfma_f32_16x16x32_bf16 v[92:95], v[64:67], v[184:187], v[92:95]
	v_mfma_f32_16x16x32_bf16 v[84:87], v[80:83], v[184:187], v[84:87]
	v_mfma_f32_16x16x32_bf16 v[156:159], v[68:71], v[164:167], v[156:159]
	v_mfma_f32_16x16x32_bf16 v[152:155], v[88:91], v[164:167], v[152:155]
	v_mfma_f32_16x16x32_bf16 v[140:143], v[68:71], v[172:175], v[140:143]
	v_mfma_f32_16x16x32_bf16 v[136:139], v[88:91], v[172:175], v[136:139]
	v_mfma_f32_16x16x32_bf16 v[116:119], v[68:71], v[180:183], v[116:119]
	v_mfma_f32_16x16x32_bf16 v[112:115], v[88:91], v[180:183], v[112:115]
	v_mfma_f32_16x16x32_bf16 v[92:95], v[68:71], v[188:191], v[92:95]
	v_mfma_f32_16x16x32_bf16 v[84:87], v[88:91], v[188:191], v[84:87]
	s_setprio 0
	s_setprio 1
	v_mfma_f32_16x16x32_bf16 v[148:151], v[100:103], v[160:163], v[148:151]
	v_mfma_f32_16x16x32_bf16 v[144:147], v[120:123], v[160:163], v[144:147]
	v_mfma_f32_16x16x32_bf16 v[128:131], v[100:103], v[168:171], v[128:131]
	v_mfma_f32_16x16x32_bf16 v[124:127], v[120:123], v[168:171], v[124:127]
	v_mfma_f32_16x16x32_bf16 v[104:107], v[100:103], v[176:179], v[104:107]
	v_mfma_f32_16x16x32_bf16 v[96:99], v[120:123], v[176:179], v[96:99]
	v_mfma_f32_16x16x32_bf16 v[76:79], v[100:103], v[184:187], v[76:79]
	v_mfma_f32_16x16x32_bf16 v[72:75], v[120:123], v[184:187], v[72:75]
	v_mfma_f32_16x16x32_bf16 v[148:151], v[108:111], v[164:167], v[148:151]
	v_mfma_f32_16x16x32_bf16 v[144:147], v[132:135], v[164:167], v[144:147]
	v_mfma_f32_16x16x32_bf16 v[128:131], v[108:111], v[172:175], v[128:131]
	v_mfma_f32_16x16x32_bf16 v[124:127], v[132:135], v[172:175], v[124:127]
	v_mfma_f32_16x16x32_bf16 v[104:107], v[108:111], v[180:183], v[104:107]
	v_mfma_f32_16x16x32_bf16 v[96:99], v[132:135], v[180:183], v[96:99]
	v_mfma_f32_16x16x32_bf16 v[76:79], v[108:111], v[188:191], v[76:79]
	v_mfma_f32_16x16x32_bf16 v[72:75], v[132:135], v[188:191], v[72:75]
	s_setprio 0
	s_barrier
	s_add_i32 s26, s52, s34
	v_lshl_add_u64 v[208:209], v[208:209], 0, s[12:13]
	s_mov_b32 m0, s26
	ds_read_b128 v[160:163], v225 offset:49152
	ds_read_b128 v[164:167], v225 offset:50176
	ds_read_b128 v[168:171], v225 offset:51200
	ds_read_b128 v[172:175], v225 offset:52224
	ds_read_b128 v[176:179], v225 offset:53248
	ds_read_b128 v[180:183], v225 offset:54272
	ds_read_b128 v[184:187], v225 offset:55296
	ds_read_b128 v[188:191], v225 offset:56320
	global_load_lds_dwordx4 v[208:209], off
	s_add_i32 m0, s26, 0x2000
	s_add_u32 s24, s24, 0x40080
	v_lshl_add_u64 v[208:209], v[210:211], 0, s[12:13]
	s_addc_u32 s25, s25, 0
	s_add_i32 s26, s53, s34
	global_load_lds_dwordx4 v[208:209], off
	v_lshl_add_u64 v[208:209], s[24:25], 0, v[194:195]
	s_mov_b32 m0, s26
	s_nop 0
	global_load_lds_dwordx4 v[208:209], off
	v_lshl_add_u64 v[208:209], s[24:25], 0, v[198:199]
	s_add_i32 m0, s26, 0x2000
	s_nop 0
	global_load_lds_dwordx4 v[208:209], off
	v_lshl_add_u64 v[208:209], v[212:213], 0, s[12:13]
	s_mov_b32 m0, s41
	s_nop 0
	global_load_lds_dwordx4 v[208:209], off
	v_lshl_add_u64 v[208:209], v[214:215], 0, s[12:13]
	s_mov_b32 m0, s42
	s_nop 0
	global_load_lds_dwordx4 v[208:209], off
	s_waitcnt vmcnt(8)
	s_waitcnt lgkmcnt(0)
	s_barrier
	s_setprio 1
	s_waitcnt lgkmcnt(0)
	v_mfma_f32_16x16x32_bf16 v[60:63], v[64:67], v[160:163], v[60:63]
	v_mfma_f32_16x16x32_bf16 v[56:59], v[80:83], v[160:163], v[56:59]
	v_mfma_f32_16x16x32_bf16 v[44:47], v[64:67], v[168:171], v[44:47]
	v_mfma_f32_16x16x32_bf16 v[40:43], v[80:83], v[168:171], v[40:43]
	v_mfma_f32_16x16x32_bf16 v[28:31], v[64:67], v[176:179], v[28:31]
	v_mfma_f32_16x16x32_bf16 v[24:27], v[80:83], v[176:179], v[24:27]
	v_mfma_f32_16x16x32_bf16 v[12:15], v[64:67], v[184:187], v[12:15]
	v_mfma_f32_16x16x32_bf16 v[8:11], v[80:83], v[184:187], v[8:11]
	v_mfma_f32_16x16x32_bf16 v[60:63], v[68:71], v[164:167], v[60:63]
	v_mfma_f32_16x16x32_bf16 v[56:59], v[88:91], v[164:167], v[56:59]
	v_mfma_f32_16x16x32_bf16 v[44:47], v[68:71], v[172:175], v[44:47]
	v_mfma_f32_16x16x32_bf16 v[40:43], v[88:91], v[172:175], v[40:43]
	v_mfma_f32_16x16x32_bf16 v[28:31], v[68:71], v[180:183], v[28:31]
	v_mfma_f32_16x16x32_bf16 v[24:27], v[88:91], v[180:183], v[24:27]
	v_mfma_f32_16x16x32_bf16 v[12:15], v[68:71], v[188:191], v[12:15]
	v_mfma_f32_16x16x32_bf16 v[8:11], v[88:91], v[188:191], v[8:11]
	s_setprio 0
	s_setprio 1
	v_mfma_f32_16x16x32_bf16 v[52:55], v[100:103], v[160:163], v[52:55]
	v_mfma_f32_16x16x32_bf16 v[48:51], v[120:123], v[160:163], v[48:51]
	v_mfma_f32_16x16x32_bf16 v[36:39], v[100:103], v[168:171], v[36:39]
	v_mfma_f32_16x16x32_bf16 v[32:35], v[120:123], v[168:171], v[32:35]
	v_mfma_f32_16x16x32_bf16 v[20:23], v[100:103], v[176:179], v[20:23]
	v_mfma_f32_16x16x32_bf16 v[16:19], v[120:123], v[176:179], v[16:19]
	v_mfma_f32_16x16x32_bf16 v[4:7], v[100:103], v[184:187], v[4:7]
	v_mfma_f32_16x16x32_bf16 v[0:3], v[120:123], v[184:187], v[0:3]
	v_mfma_f32_16x16x32_bf16 v[52:55], v[108:111], v[164:167], v[52:55]
	v_mfma_f32_16x16x32_bf16 v[48:51], v[132:135], v[164:167], v[48:51]
	v_mfma_f32_16x16x32_bf16 v[36:39], v[108:111], v[172:175], v[36:39]
	v_mfma_f32_16x16x32_bf16 v[32:35], v[132:135], v[172:175], v[32:35]
	v_mfma_f32_16x16x32_bf16 v[20:23], v[108:111], v[180:183], v[20:23]
	v_mfma_f32_16x16x32_bf16 v[16:19], v[132:135], v[180:183], v[16:19]
	v_mfma_f32_16x16x32_bf16 v[4:7], v[108:111], v[188:191], v[4:7]
	v_mfma_f32_16x16x32_bf16 v[0:3], v[132:135], v[188:191], v[0:3]
	s_setprio 0
	s_barrier
	s_add_i32 s51, s51, 2
	s_add_u32 s17, s17, 0x100
	s_addc_u32 s50, s50, 0
	s_add_u32 s22, s22, 0x100
	s_addc_u32 s23, s23, 0
	s_cmp_gt_u32 s51, 13
	s_cbranch_scc0 .LBB0_877
	s_and_b64 vcc, exec, s[14:15]
	s_cbranch_vccz .LBB0_880
	s_barrier
.LBB0_880:
	s_mov_b32 s99, 1
	v_lshlrev_b32_e32 v252, 4, v216
	v_add_u32_e32 v252, 0x21000, v252
	s_mov_b32 s98, s7
	s_cmp_eq_u32 s98, 0
	s_cbranch_scc1 .Lf1e_201
	s_lshl_b32 s99, s6, 8
	v_add_u32_e32 v253, s99, v217
	v_add_u32_e32 v253, 0x80, v253
	v_lshlrev_b32_e32 v253, 12, v253
	v_lshl_or_b32 v254, s49, 8, v222
	v_lshl_add_u32 v253, v254, 1, v253
	global_load_dwordx4 v[132:135], v253, s[10:11]
	global_load_dwordx4 v[120:123], v253, s[10:11] offset:256
	v_add_u32_e32 v254, 0x10000, v253
	global_load_dwordx4 v[108:111], v254, s[10:11]
	global_load_dwordx4 v[100:103], v254, s[10:11] offset:256
	v_add_u32_e32 v254, 0x20000, v253
	global_load_dwordx4 v[88:91], v254, s[10:11]
	global_load_dwordx4 v[80:83], v254, s[10:11] offset:256

.LBB0_1911:
	s_cmp_lt_i32 s94, 15
	s_cselect_b64 s[0:1], -1, 0
	s_cmp_gt_i32 s95, 14
	s_cselect_b64 s[2:3], -1, 0
	s_and_b64 s[0:1], s[0:1], s[2:3]
	s_andn2_b64 vcc, exec, s[0:1]
	s_cbranch_vccnz .LBB0_2052
	s_mov_b32 s99, 0
	s_mov_b64 s[0:1], s[76:77]
	s_waitcnt lgkmcnt(0)
	s_load_dwordx2 s[4:5], s[0:1], 0xb0
	s_mov_b64 s[0:1], s[76:77]
	s_waitcnt vmcnt(0)
	v_mov_b32_e32 v0, v216
	s_load_dword s0, s[76:77], 0xc0
	s_add_u32 s2, s76, 0xc0
	s_addc_u32 s3, s77, 0
	s_waitcnt lgkmcnt(0)
	s_add_u32 s29, s4, 0x2bb00000
	s_addc_u32 s30, s5, 0
	s_add_u32 s31, s4, 0x2400000
	s_mov_b32 s1, s0
	s_mov_b32 s28, s72
	s_addc_u32 s33, s5, 0
	v_mov_b32_e32 v8, v216
	s_cmpk_lt_i32 s28, 0x200
	s_cselect_b64 s[8:9], -1, 0
	s_cmpk_gt_i32 s28, 0x1ff
	v_readfirstlane_b32 s14, v8
	s_cbranch_scc1 .LBB0_1915
	s_ashr_i32 s6, s28, 31
	s_lshr_b32 s6, s6, 29
	s_add_i32 s12, s28, s6
	s_and_b32 s6, s12, -8
	s_sub_i32 s10, s28, s6
	s_cmp_gt_i32 s10, -1
	s_cbranch_scc0 .LBB0_1916
	s_lshl_b32 s11, s10, 6
	s_ashr_i32 s6, s12, 3
	s_cbranch_execz .LBB0_1917
	s_branch .LBB0_1918
